# combined: phase-split GEMM loops + NA batched/double-buffered mask reads + router unroll + batched loads in out-proj and hyena order-0 epilogues
# speedup vs baseline: 1.0131x; 1.0063x over previous
; __device__ __forceinline__ float bf2f(u16 h) { return __uint_as_float(((unsigned)h) << 16); }
; __device__ __forceinline__ void hyena_item(const Params& p, int item, int order, char* lds) {
;     ...
; #pragma unroll 2
;     for (int kk = 0; kk < 64; ++kk) {
;       const int kn = (kk + 1 < 64) ? kk + 1 : kk;
;       const bf16x8 bnext = *(const bf16x8*)(bbase + kn * 64);
;       const bf16x8 n0 = *(const bf16x8*)(abase + (32 * kn - 16 * bt) * 2);
;       const bf16x8 n1 = *(const bf16x8*)(abase + (32 * kn - 16 * (bt + 1)) * 2);
; #pragma unroll
;       for (int i = 0; i < 8; ++i) acc[i] = __builtin_amdgcn_mfma_f32_16x16x32_bf16(fr[i], bcur, acc[i], 0, 0, 0);
; #pragma unroll
;       for (int i = 7; i >= 2; --i) fr[i] = fr[i - 2];
;       fr[0] = n0; fr[1] = n1; bcur = bnext;
;     }
; #pragma unroll
;     for (int i = 0; i < 8; ++i) {
;       const int t = (bt + i) * 16 + lq * 4;
;       union { uint2 v; u16 e[4]; } xz, uu;
;       xz.v = *(const uint2*)(xsrc + t);
;       uu.v = *(const uint2*)(U + lr * 2056 + t);
;       float zz[6];
;       {
;         const float zl = bf2f(xsrc[max(t - 1, 0)]), zr = bf2f(xsrc[min(t + 4, 2047)]);
;         zz[0] = (t > 0) ? zl : 0.f;
;         zz[5] = (t + 4 < 2048) ? zr : 0.f;
;       }
.LBB0_659:
	ds_read_b128 v[76:79], v76
	ds_read_b128 v[80:83], v75
	ds_read_b128 v[84:87], v74
	s_add_i32 s9, s8, 0x1080
	s_cmpk_lg_i32 s8, 0xff80
	s_waitcnt lgkmcnt(2)
	v_mfma_f32_16x16x32_bf16 v[0:3], v[48:51], v[76:79], v[0:3]
	v_add_u32_e32 v48, s8, v66
	v_add_u32_e32 v49, s8, v73
	ds_read_b128 v[88:91], v48 offset:4160
	v_add_u32_e32 v48, 0x12140, v49
	ds_read_b128 v[92:95], v48
	v_add_u32_e32 v48, 0x12120, v49
	ds_read_b128 v[96:99], v48
	v_mfma_f32_16x16x32_bf16 v[20:23], v[32:35], v[76:79], v[20:23]
	s_cselect_b32 s9, s9, 0xfc0
	v_mov_b64_e32 v[50:51], v[38:39]
	s_addk_i32 s8, 0x80
	v_mfma_f32_16x16x32_bf16 v[16:19], v[36:39], v[76:79], v[16:19]
	v_mov_b64_e32 v[48:49], v[36:37]
	s_cmp_lg_u32 s8, 0
	v_mfma_f32_16x16x32_bf16 v[12:15], v[44:47], v[76:79], v[12:15]
	v_mfma_f32_16x16x32_bf16 v[8:11], v[40:43], v[76:79], v[8:11]
	v_mfma_f32_16x16x32_bf16 v[4:7], v[52:55], v[76:79], v[4:7]
	v_mov_b64_e32 v[54:55], v[34:35]
	v_mov_b64_e32 v[52:53], v[32:33]
	s_waitcnt lgkmcnt(4)
	v_mfma_f32_16x16x32_bf16 v[28:31], v[80:83], v[76:79], v[28:31]
	s_waitcnt lgkmcnt(3)
	v_mfma_f32_16x16x32_bf16 v[24:27], v[84:87], v[76:79], v[24:27]
	v_add_u32_e32 v76, s9, v66
	s_waitcnt lgkmcnt(2)
	v_mfma_f32_16x16x32_bf16 v[20:23], v[80:83], v[88:91], v[20:23]
	v_mfma_f32_16x16x32_bf16 v[16:19], v[84:87], v[88:91], v[16:19]
	v_mfma_f32_16x16x32_bf16 v[12:15], v[32:35], v[88:91], v[12:15]
	s_waitcnt lgkmcnt(1)
	v_mov_b64_e32 v[32:33], v[92:93]
	v_mov_b64_e32 v[34:35], v[94:95]
	v_mfma_f32_16x16x32_bf16 v[8:11], v[36:39], v[88:91], v[8:11]
	s_waitcnt lgkmcnt(0)
	v_mov_b64_e32 v[36:37], v[96:97]
	v_mov_b64_e32 v[38:39], v[98:99]
	v_mfma_f32_16x16x32_bf16 v[4:7], v[44:47], v[88:91], v[4:7]
	v_sub_u32_e32 v44, s9, v72
	v_add_u32_e32 v75, v65, v44
	v_mov_b64_e32 v[44:45], v[80:81]
	v_mfma_f32_16x16x32_bf16 v[0:3], v[40:43], v[88:91], v[0:3]
	v_mov_b64_e32 v[40:41], v[84:85]
	v_subrev_u32_e32 v74, 32, v75
	v_mov_b64_e32 v[42:43], v[86:87]
	v_mfma_f32_16x16x32_bf16 v[28:31], v[92:95], v[88:91], v[28:31]
	v_mov_b64_e32 v[46:47], v[82:83]
	v_mfma_f32_16x16x32_bf16 v[24:27], v[96:99], v[88:91], v[24:27]
	s_cbranch_scc1 .LBB0_659
	v_lshl_or_b32 v32, v71, 4, v68
	v_mov_b32_e32 v133, 0
	v_mov_b32_e32 v135, 0
	v_mov_b32_e32 v137, 0
	v_lshlrev_b32_e32 v132, 1, v32
	v_max_i32_e32 v134, 1, v32
	v_min_i32_e32 v136, 0x7fb, v32
	v_lshlrev_b32_e32 v134, 1, v134
	v_lshlrev_b32_e32 v136, 1, v136
	v_lshl_add_u64 v[138:139], v[56:57], 0, v[132:133]
	v_lshl_add_u64 v[140:141], v[56:57], 0, v[134:135]
	v_lshl_add_u64 v[142:143], v[56:57], 0, v[136:137]
	global_load_dwordx2 v[100:101], v[138:139], off
	global_load_ushort v116, v[140:141], off offset:-2
	global_load_ushort v124, v[142:143], off offset:8
	v_add_u32_e32 v253, v69, v132
	ds_read_b64 v[236:237], v253
	v_or_b32_e32 v252, 16, v32
	v_lshlrev_b32_e32 v132, 1, v252
	v_max_i32_e32 v134, 1, v252
	v_min_i32_e32 v136, 0x7fb, v252
	v_lshlrev_b32_e32 v134, 1, v134
	v_lshlrev_b32_e32 v136, 1, v136
	v_lshl_add_u64 v[138:139], v[56:57], 0, v[132:133]
	v_lshl_add_u64 v[140:141], v[56:57], 0, v[134:135]
	v_lshl_add_u64 v[142:143], v[56:57], 0, v[136:137]
	global_load_dwordx2 v[102:103], v[138:139], off
	global_load_ushort v117, v[140:141], off offset:-2
	global_load_ushort v125, v[142:143], off offset:8
	v_add_u32_e32 v253, v69, v132
	ds_read_b64 v[238:239], v253
	v_or_b32_e32 v252, 32, v32
	v_lshlrev_b32_e32 v132, 1, v252
	v_max_i32_e32 v134, 1, v252
	v_min_i32_e32 v136, 0x7fb, v252
	v_lshlrev_b32_e32 v134, 1, v134
	v_lshlrev_b32_e32 v136, 1, v136
	v_lshl_add_u64 v[138:139], v[56:57], 0, v[132:133]
	v_lshl_add_u64 v[140:141], v[56:57], 0, v[134:135]
	v_lshl_add_u64 v[142:143], v[56:57], 0, v[136:137]
	global_load_dwordx2 v[104:105], v[138:139], off
	global_load_ushort v118, v[140:141], off offset:-2
	global_load_ushort v126, v[142:143], off offset:8
	v_add_u32_e32 v253, v69, v132
	ds_read_b64 v[240:241], v253
	v_or_b32_e32 v252, 48, v32
	v_lshlrev_b32_e32 v132, 1, v252
	v_max_i32_e32 v134, 1, v252
	v_min_i32_e32 v136, 0x7fb, v252
	v_lshlrev_b32_e32 v134, 1, v134
	v_lshlrev_b32_e32 v136, 1, v136
	v_lshl_add_u64 v[138:139], v[56:57], 0, v[132:133]
	v_lshl_add_u64 v[140:141], v[56:57], 0, v[134:135]
	v_lshl_add_u64 v[142:143], v[56:57], 0, v[136:137]
	global_load_dwordx2 v[106:107], v[138:139], off
	global_load_ushort v119, v[140:141], off offset:-2
	global_load_ushort v127, v[142:143], off offset:8
	v_add_u32_e32 v253, v69, v132
	ds_read_b64 v[242:243], v253
	v_or_b32_e32 v252, 64, v32
	v_lshlrev_b32_e32 v132, 1, v252
	v_max_i32_e32 v134, 1, v252
	v_min_i32_e32 v136, 0x7fb, v252
	v_lshlrev_b32_e32 v134, 1, v134
	v_lshlrev_b32_e32 v136, 1, v136
	v_lshl_add_u64 v[138:139], v[56:57], 0, v[132:133]
	v_lshl_add_u64 v[140:141], v[56:57], 0, v[134:135]
	v_lshl_add_u64 v[142:143], v[56:57], 0, v[136:137]
	global_load_dwordx2 v[108:109], v[138:139], off
	global_load_ushort v120, v[140:141], off offset:-2
	global_load_ushort v128, v[142:143], off offset:8
	v_add_u32_e32 v253, v69, v132
	ds_read_b64 v[244:245], v253
	v_or_b32_e32 v252, 80, v32
	v_lshlrev_b32_e32 v132, 1, v252
	v_max_i32_e32 v134, 1, v252
	v_min_i32_e32 v136, 0x7fb, v252
	v_lshlrev_b32_e32 v134, 1, v134
	v_lshlrev_b32_e32 v136, 1, v136
	v_lshl_add_u64 v[138:139], v[56:57], 0, v[132:133]
	v_lshl_add_u64 v[140:141], v[56:57], 0, v[134:135]
	v_lshl_add_u64 v[142:143], v[56:57], 0, v[136:137]
	global_load_dwordx2 v[110:111], v[138:139], off
	global_load_ushort v121, v[140:141], off offset:-2
	global_load_ushort v129, v[142:143], off offset:8
	v_add_u32_e32 v253, v69, v132
	ds_read_b64 v[246:247], v253
	v_or_b32_e32 v252, 96, v32
	v_lshlrev_b32_e32 v132, 1, v252
	v_max_i32_e32 v134, 1, v252
	v_min_i32_e32 v136, 0x7fb, v252
	v_lshlrev_b32_e32 v134, 1, v134
	v_lshlrev_b32_e32 v136, 1, v136
	v_lshl_add_u64 v[138:139], v[56:57], 0, v[132:133]
	v_lshl_add_u64 v[140:141], v[56:57], 0, v[134:135]
	v_lshl_add_u64 v[142:143], v[56:57], 0, v[136:137]
	global_load_dwordx2 v[112:113], v[138:139], off
	global_load_ushort v122, v[140:141], off offset:-2
	global_load_ushort v130, v[142:143], off offset:8
	v_add_u32_e32 v253, v69, v132
	ds_read_b64 v[248:249], v253
	v_or_b32_e32 v252, 112, v32
	v_lshlrev_b32_e32 v132, 1, v252
	v_max_i32_e32 v134, 1, v252
	v_min_i32_e32 v136, 0x7fb, v252
	v_lshlrev_b32_e32 v134, 1, v134
	v_lshlrev_b32_e32 v136, 1, v136
	v_lshl_add_u64 v[138:139], v[56:57], 0, v[132:133]
	v_lshl_add_u64 v[140:141], v[56:57], 0, v[134:135]
	v_lshl_add_u64 v[142:143], v[56:57], 0, v[136:137]
	global_load_dwordx2 v[114:115], v[138:139], off
	global_load_ushort v123, v[140:141], off offset:-2
	global_load_ushort v131, v[142:143], off offset:8
	v_add_u32_e32 v253, v69, v132
	ds_read_b64 v[250:251], v253
	s_mov_b32 s9, 8
	s_waitcnt vmcnt(21)
; __device__ __forceinline__ float bf2f(u16 h) { return __uint_as_float(((unsigned)h) << 16); }
; __device__ __forceinline__ void hyena_item(const Params& p, int item, int order, char* lds) {
;     ...
; #pragma unroll
;     for (int i = 0; i < 8; ++i) {
;       const int t = (bt + i) * 16 + lq * 4;
;       union { uint2 v; u16 e[4]; } xz, uu;
;       xz.v = *(const uint2*)(xsrc + t);
;       uu.v = *(const uint2*)(U + lr * 2056 + t);
;       float zz[6];
;       {
;         const float zl = bf2f(xsrc[max(t - 1, 0)]), zr = bf2f(xsrc[min(t + 4, 2047)]);
;         zz[0] = (t > 0) ? zl : 0.f;
;         zz[5] = (t + 4 < 2048) ? zr : 0.f;
;       }
; #pragma unroll
;       for (int e = 0; e < 4; ++e) zz[e + 1] = bf2f(xz.e[e]);
;       float y[4];
; #pragma unroll
;       for (int e = 0; e < 4; ++e) {
;         const float xg = xsb + xw0 * zz[e] + xw1 * zz[e + 1] + xw2 * zz[e + 2];
;         y[e] = xg * (acc[i][e] + skipv * bf2f(uu.e[e]));
;       }
;       {
;         uint2 ov; ov.x = pack2(y[0], y[1]); ov.y = pack2(y[2], y[3]);
;         *(uint2*)((u16*)(p.ws + OFF_Y1T) + ((size_t)(b * 512 + c)) * 2048 + t) = ov;
;       }
;     }
	s_waitcnt lgkmcnt(7)
	v_and_b32_e32 v132, 0xffff0000, v236
	v_lshlrev_b32_e32 v133, 16, v236
	v_alignbit_b32 v134, v237, v236, 16
	v_and_b32_e32 v135, 0xffff0000, v237
	v_fma_f32 v29, v62, v132, v29
	v_and_b32_e32 v134, 0xffff0000, v134
	v_fmac_f32_e32 v31, v62, v135
	v_fma_f32 v30, v62, v134, v30
	v_fma_f32 v28, v62, v133, v28
	v_cmp_lt_i32_e32 vcc, 0, v32
	v_and_b32_e32 v136, 0xffff0000, v100
	v_lshlrev_b32_e32 v137, 16, v116
	v_lshlrev_b32_e32 v138, 16, v100
	v_alignbit_b32 v139, v101, v100, 16
	v_cndmask_b32_e32 v137, 0, v137, vcc
	v_lshlrev_b32_e32 v140, 16, v124
	v_and_b32_e32 v139, 0xffff0000, v139
	v_fma_f32 v141, v60, v138, v61
	v_fma_f32 v137, v60, v137, v61
	v_and_b32_e32 v142, 0xffff0000, v101
	v_cmp_gt_i32_e32 vcc, s77, v32
	v_fma_f32 v143, v60, v136, v61
	v_fmac_f32_e32 v141, v63, v136
	v_fma_f32 v254, v60, v139, v61
	v_fmac_f32_e32 v137, v63, v138
	v_cndmask_b32_e32 v140, 0, v140, vcc
	v_fmac_f32_e32 v143, v63, v139
	v_fmac_f32_e32 v141, v64, v139
	v_fmac_f32_e32 v254, v63, v142
	v_fmac_f32_e32 v137, v64, v136
	v_fmac_f32_e32 v143, v64, v142
	v_mul_f32_e32 v29, v29, v141
	v_fmac_f32_e32 v254, v64, v140
	v_mul_f32_e32 v28, v28, v137
	v_mul_f32_e32 v30, v143, v30
	v_mul_f32_e32 v31, v31, v254
	v_lshlrev_b32_e32 v132, 1, v32
	v_mov_b32_e32 v133, 0
	v_cvt_pk_bf16_f32 v28, v28, v29
	v_cvt_pk_bf16_f32 v29, v30, v31
	v_lshl_add_u64 v[134:135], v[58:59], 0, v[132:133]
	global_store_dwordx2 v[134:135], v[28:29], off
	v_or_b32_e32 v252, 16, v32
	s_waitcnt vmcnt(19)
	s_waitcnt lgkmcnt(6)
	v_and_b32_e32 v132, 0xffff0000, v238
	v_lshlrev_b32_e32 v133, 16, v238
	v_alignbit_b32 v134, v239, v238, 16
	v_and_b32_e32 v135, 0xffff0000, v239
	v_fma_f32 v25, v62, v132, v25
	v_and_b32_e32 v134, 0xffff0000, v134
	v_fmac_f32_e32 v27, v62, v135
	v_fma_f32 v26, v62, v134, v26
	v_fma_f32 v24, v62, v133, v24
	v_cmp_lt_i32_e32 vcc, 0, v252
	v_and_b32_e32 v136, 0xffff0000, v102
	v_lshlrev_b32_e32 v137, 16, v117
	v_lshlrev_b32_e32 v138, 16, v102
	v_alignbit_b32 v139, v103, v102, 16
	v_cndmask_b32_e32 v137, 0, v137, vcc
	v_lshlrev_b32_e32 v140, 16, v125
	v_and_b32_e32 v139, 0xffff0000, v139
	v_fma_f32 v141, v60, v138, v61
	v_fma_f32 v137, v60, v137, v61
	v_and_b32_e32 v142, 0xffff0000, v103
	v_cmp_gt_i32_e32 vcc, s77, v252
	v_fma_f32 v143, v60, v136, v61
	v_fmac_f32_e32 v141, v63, v136
	v_fma_f32 v254, v60, v139, v61
	v_fmac_f32_e32 v137, v63, v138
	v_cndmask_b32_e32 v140, 0, v140, vcc
	v_fmac_f32_e32 v143, v63, v139
	v_fmac_f32_e32 v141, v64, v139
	v_fmac_f32_e32 v254, v63, v142
	v_fmac_f32_e32 v137, v64, v136
	v_fmac_f32_e32 v143, v64, v142
	v_mul_f32_e32 v25, v25, v141
	v_fmac_f32_e32 v254, v64, v140
	v_mul_f32_e32 v24, v24, v137
	v_mul_f32_e32 v26, v143, v26
	v_mul_f32_e32 v27, v27, v254
	v_lshlrev_b32_e32 v132, 1, v252
	v_mov_b32_e32 v133, 0
	v_cvt_pk_bf16_f32 v24, v24, v25
	v_cvt_pk_bf16_f32 v25, v26, v27
	v_lshl_add_u64 v[134:135], v[58:59], 0, v[132:133]
	global_store_dwordx2 v[134:135], v[24:25], off
	v_or_b32_e32 v252, 32, v32
	s_waitcnt vmcnt(17)
	s_waitcnt lgkmcnt(5)
	v_and_b32_e32 v132, 0xffff0000, v240
	v_lshlrev_b32_e32 v133, 16, v240
	v_alignbit_b32 v134, v241, v240, 16
	v_and_b32_e32 v135, 0xffff0000, v241
	v_fma_f32 v21, v62, v132, v21
	v_and_b32_e32 v134, 0xffff0000, v134
	v_fmac_f32_e32 v23, v62, v135
	v_fma_f32 v22, v62, v134, v22
	v_fma_f32 v20, v62, v133, v20
	v_cmp_lt_i32_e32 vcc, 0, v252
	v_and_b32_e32 v136, 0xffff0000, v104
	v_lshlrev_b32_e32 v137, 16, v118
	v_lshlrev_b32_e32 v138, 16, v104
	v_alignbit_b32 v139, v105, v104, 16
	v_cndmask_b32_e32 v137, 0, v137, vcc
	v_lshlrev_b32_e32 v140, 16, v126
	v_and_b32_e32 v139, 0xffff0000, v139
	v_fma_f32 v141, v60, v138, v61
	v_fma_f32 v137, v60, v137, v61
	v_and_b32_e32 v142, 0xffff0000, v105
	v_cmp_gt_i32_e32 vcc, s77, v252
	v_fma_f32 v143, v60, v136, v61
	v_fmac_f32_e32 v141, v63, v136
	v_fma_f32 v254, v60, v139, v61
	v_fmac_f32_e32 v137, v63, v138
	v_cndmask_b32_e32 v140, 0, v140, vcc
	v_fmac_f32_e32 v143, v63, v139
	v_fmac_f32_e32 v141, v64, v139
	v_fmac_f32_e32 v254, v63, v142
	v_fmac_f32_e32 v137, v64, v136
	v_fmac_f32_e32 v143, v64, v142
	v_mul_f32_e32 v21, v21, v141
	v_fmac_f32_e32 v254, v64, v140
	v_mul_f32_e32 v20, v20, v137
	v_mul_f32_e32 v22, v143, v22
	v_mul_f32_e32 v23, v23, v254
	v_lshlrev_b32_e32 v132, 1, v252
	v_mov_b32_e32 v133, 0
	v_cvt_pk_bf16_f32 v20, v20, v21
	v_cvt_pk_bf16_f32 v21, v22, v23
	v_lshl_add_u64 v[134:135], v[58:59], 0, v[132:133]
	global_store_dwordx2 v[134:135], v[20:21], off
	v_or_b32_e32 v252, 48, v32
	s_waitcnt vmcnt(15)
	s_waitcnt lgkmcnt(4)
	v_and_b32_e32 v132, 0xffff0000, v242
	v_lshlrev_b32_e32 v133, 16, v242
	v_alignbit_b32 v134, v243, v242, 16
	v_and_b32_e32 v135, 0xffff0000, v243
	v_fma_f32 v17, v62, v132, v17
	v_and_b32_e32 v134, 0xffff0000, v134
	v_fmac_f32_e32 v19, v62, v135
	v_fma_f32 v18, v62, v134, v18
	v_fma_f32 v16, v62, v133, v16
	v_cmp_lt_i32_e32 vcc, 0, v252
	v_and_b32_e32 v136, 0xffff0000, v106
	v_lshlrev_b32_e32 v137, 16, v119
	v_lshlrev_b32_e32 v138, 16, v106
	v_alignbit_b32 v139, v107, v106, 16
	v_cndmask_b32_e32 v137, 0, v137, vcc
	v_lshlrev_b32_e32 v140, 16, v127
	v_and_b32_e32 v139, 0xffff0000, v139
	v_fma_f32 v141, v60, v138, v61
	v_fma_f32 v137, v60, v137, v61
	v_and_b32_e32 v142, 0xffff0000, v107
	v_cmp_gt_i32_e32 vcc, s77, v252
	v_fma_f32 v143, v60, v136, v61
	v_fmac_f32_e32 v141, v63, v136
	v_fma_f32 v254, v60, v139, v61
	v_fmac_f32_e32 v137, v63, v138
	v_cndmask_b32_e32 v140, 0, v140, vcc
	v_fmac_f32_e32 v143, v63, v139
	v_fmac_f32_e32 v141, v64, v139
	v_fmac_f32_e32 v254, v63, v142
	v_fmac_f32_e32 v137, v64, v136
	v_fmac_f32_e32 v143, v64, v142
	v_mul_f32_e32 v17, v17, v141
	v_fmac_f32_e32 v254, v64, v140
	v_mul_f32_e32 v16, v16, v137
	v_mul_f32_e32 v18, v143, v18
	v_mul_f32_e32 v19, v19, v254
	v_lshlrev_b32_e32 v132, 1, v252
	v_mov_b32_e32 v133, 0
	v_cvt_pk_bf16_f32 v16, v16, v17
	v_cvt_pk_bf16_f32 v17, v18, v19
	v_lshl_add_u64 v[134:135], v[58:59], 0, v[132:133]
	global_store_dwordx2 v[134:135], v[16:17], off
	v_or_b32_e32 v252, 64, v32
	s_waitcnt vmcnt(13)
; __device__ __forceinline__ float bf2f(u16 h) { return __uint_as_float(((unsigned)h) << 16); }
; __device__ __forceinline__ void hyena_item(const Params& p, int item, int order, char* lds) {
;     ...
; #pragma unroll
;     for (int i = 0; i < 8; ++i) {
;       const int t = (bt + i) * 16 + lq * 4;
;       union { uint2 v; u16 e[4]; } xz, uu;
;       xz.v = *(const uint2*)(xsrc + t);
;       uu.v = *(const uint2*)(U + lr * 2056 + t);
;       float zz[6];
;       {
;         const float zl = bf2f(xsrc[max(t - 1, 0)]), zr = bf2f(xsrc[min(t + 4, 2047)]);
;         zz[0] = (t > 0) ? zl : 0.f;
;         zz[5] = (t + 4 < 2048) ? zr : 0.f;
;       }
; #pragma unroll
;       for (int e = 0; e < 4; ++e) zz[e + 1] = bf2f(xz.e[e]);
;       float y[4];
; #pragma unroll
;       for (int e = 0; e < 4; ++e) {
;         const float xg = xsb + xw0 * zz[e] + xw1 * zz[e + 1] + xw2 * zz[e + 2];
;         y[e] = xg * (acc[i][e] + skipv * bf2f(uu.e[e]));
;       }
;       {
;         uint2 ov; ov.x = pack2(y[0], y[1]); ov.y = pack2(y[2], y[3]);
;         *(uint2*)((u16*)(p.ws + OFF_Y1T) + ((size_t)(b * 512 + c)) * 2048 + t) = ov;
;       }
;     }
	s_waitcnt lgkmcnt(3)
	v_and_b32_e32 v132, 0xffff0000, v244
	v_lshlrev_b32_e32 v133, 16, v244
	v_alignbit_b32 v134, v245, v244, 16
	v_and_b32_e32 v135, 0xffff0000, v245
	v_fma_f32 v13, v62, v132, v13
	v_and_b32_e32 v134, 0xffff0000, v134
	v_fmac_f32_e32 v15, v62, v135
	v_fma_f32 v14, v62, v134, v14
	v_fma_f32 v12, v62, v133, v12
	v_cmp_lt_i32_e32 vcc, 0, v252
	v_and_b32_e32 v136, 0xffff0000, v108
	v_lshlrev_b32_e32 v137, 16, v120
	v_lshlrev_b32_e32 v138, 16, v108
	v_alignbit_b32 v139, v109, v108, 16
	v_cndmask_b32_e32 v137, 0, v137, vcc
	v_lshlrev_b32_e32 v140, 16, v128
	v_and_b32_e32 v139, 0xffff0000, v139
	v_fma_f32 v141, v60, v138, v61
	v_fma_f32 v137, v60, v137, v61
	v_and_b32_e32 v142, 0xffff0000, v109
	v_cmp_gt_i32_e32 vcc, s77, v252
	v_fma_f32 v143, v60, v136, v61
	v_fmac_f32_e32 v141, v63, v136
	v_fma_f32 v254, v60, v139, v61
	v_fmac_f32_e32 v137, v63, v138
	v_cndmask_b32_e32 v140, 0, v140, vcc
	v_fmac_f32_e32 v143, v63, v139
	v_fmac_f32_e32 v141, v64, v139
	v_fmac_f32_e32 v254, v63, v142
	v_fmac_f32_e32 v137, v64, v136
	v_fmac_f32_e32 v143, v64, v142
	v_mul_f32_e32 v13, v13, v141
	v_fmac_f32_e32 v254, v64, v140
	v_mul_f32_e32 v12, v12, v137
	v_mul_f32_e32 v14, v143, v14
	v_mul_f32_e32 v15, v15, v254
	v_lshlrev_b32_e32 v132, 1, v252
	v_mov_b32_e32 v133, 0
	v_cvt_pk_bf16_f32 v12, v12, v13
	v_cvt_pk_bf16_f32 v13, v14, v15
	v_lshl_add_u64 v[134:135], v[58:59], 0, v[132:133]
	global_store_dwordx2 v[134:135], v[12:13], off
	v_or_b32_e32 v252, 80, v32
	s_waitcnt vmcnt(11)
	s_waitcnt lgkmcnt(2)
	v_and_b32_e32 v132, 0xffff0000, v246
	v_lshlrev_b32_e32 v133, 16, v246
	v_alignbit_b32 v134, v247, v246, 16
	v_and_b32_e32 v135, 0xffff0000, v247
	v_fma_f32 v9, v62, v132, v9
	v_and_b32_e32 v134, 0xffff0000, v134
	v_fmac_f32_e32 v11, v62, v135
	v_fma_f32 v10, v62, v134, v10
	v_fma_f32 v8, v62, v133, v8
	v_cmp_lt_i32_e32 vcc, 0, v252
	v_and_b32_e32 v136, 0xffff0000, v110
	v_lshlrev_b32_e32 v137, 16, v121
	v_lshlrev_b32_e32 v138, 16, v110
	v_alignbit_b32 v139, v111, v110, 16
	v_cndmask_b32_e32 v137, 0, v137, vcc
	v_lshlrev_b32_e32 v140, 16, v129
	v_and_b32_e32 v139, 0xffff0000, v139
	v_fma_f32 v141, v60, v138, v61
	v_fma_f32 v137, v60, v137, v61
	v_and_b32_e32 v142, 0xffff0000, v111
	v_cmp_gt_i32_e32 vcc, s77, v252
	v_fma_f32 v143, v60, v136, v61
	v_fmac_f32_e32 v141, v63, v136
	v_fma_f32 v254, v60, v139, v61
	v_fmac_f32_e32 v137, v63, v138
	v_cndmask_b32_e32 v140, 0, v140, vcc
	v_fmac_f32_e32 v143, v63, v139
	v_fmac_f32_e32 v141, v64, v139
	v_fmac_f32_e32 v254, v63, v142
	v_fmac_f32_e32 v137, v64, v136
	v_fmac_f32_e32 v143, v64, v142
	v_mul_f32_e32 v9, v9, v141
	v_fmac_f32_e32 v254, v64, v140
	v_mul_f32_e32 v8, v8, v137
	v_mul_f32_e32 v10, v143, v10
	v_mul_f32_e32 v11, v11, v254
	v_lshlrev_b32_e32 v132, 1, v252
	v_mov_b32_e32 v133, 0
	v_cvt_pk_bf16_f32 v8, v8, v9
	v_cvt_pk_bf16_f32 v9, v10, v11
	v_lshl_add_u64 v[134:135], v[58:59], 0, v[132:133]
	global_store_dwordx2 v[134:135], v[8:9], off
	v_or_b32_e32 v252, 96, v32
	s_waitcnt vmcnt(9)
	s_waitcnt lgkmcnt(1)
	v_and_b32_e32 v132, 0xffff0000, v248
	v_lshlrev_b32_e32 v133, 16, v248
	v_alignbit_b32 v134, v249, v248, 16
	v_and_b32_e32 v135, 0xffff0000, v249
	v_fma_f32 v5, v62, v132, v5
	v_and_b32_e32 v134, 0xffff0000, v134
	v_fmac_f32_e32 v7, v62, v135
	v_fma_f32 v6, v62, v134, v6
	v_fma_f32 v4, v62, v133, v4
	v_cmp_lt_i32_e32 vcc, 0, v252
	v_and_b32_e32 v136, 0xffff0000, v112
	v_lshlrev_b32_e32 v137, 16, v122
	v_lshlrev_b32_e32 v138, 16, v112
	v_alignbit_b32 v139, v113, v112, 16
	v_cndmask_b32_e32 v137, 0, v137, vcc
	v_lshlrev_b32_e32 v140, 16, v130
	v_and_b32_e32 v139, 0xffff0000, v139
	v_fma_f32 v141, v60, v138, v61
	v_fma_f32 v137, v60, v137, v61
	v_and_b32_e32 v142, 0xffff0000, v113
	v_cmp_gt_i32_e32 vcc, s77, v252
	v_fma_f32 v143, v60, v136, v61
	v_fmac_f32_e32 v141, v63, v136
	v_fma_f32 v254, v60, v139, v61
	v_fmac_f32_e32 v137, v63, v138
	v_cndmask_b32_e32 v140, 0, v140, vcc
	v_fmac_f32_e32 v143, v63, v139
	v_fmac_f32_e32 v141, v64, v139
	v_fmac_f32_e32 v254, v63, v142
	v_fmac_f32_e32 v137, v64, v136
	v_fmac_f32_e32 v143, v64, v142
	v_mul_f32_e32 v5, v5, v141
	v_fmac_f32_e32 v254, v64, v140
	v_mul_f32_e32 v4, v4, v137
	v_mul_f32_e32 v6, v143, v6
	v_mul_f32_e32 v7, v7, v254
	v_lshlrev_b32_e32 v132, 1, v252
	v_mov_b32_e32 v133, 0
	v_cvt_pk_bf16_f32 v4, v4, v5
	v_cvt_pk_bf16_f32 v5, v6, v7
	v_lshl_add_u64 v[134:135], v[58:59], 0, v[132:133]
	global_store_dwordx2 v[134:135], v[4:5], off
	v_or_b32_e32 v252, 112, v32
	s_waitcnt vmcnt(7)
	s_waitcnt lgkmcnt(0)
	v_and_b32_e32 v132, 0xffff0000, v250
	v_lshlrev_b32_e32 v133, 16, v250
	v_alignbit_b32 v134, v251, v250, 16
	v_and_b32_e32 v135, 0xffff0000, v251
	v_fma_f32 v1, v62, v132, v1
	v_and_b32_e32 v134, 0xffff0000, v134
	v_fmac_f32_e32 v3, v62, v135
	v_fma_f32 v2, v62, v134, v2
	v_fma_f32 v0, v62, v133, v0
	v_cmp_lt_i32_e32 vcc, 0, v252
	v_and_b32_e32 v136, 0xffff0000, v114
	v_lshlrev_b32_e32 v137, 16, v123
	v_lshlrev_b32_e32 v138, 16, v114
	v_alignbit_b32 v139, v115, v114, 16
	v_cndmask_b32_e32 v137, 0, v137, vcc
	v_lshlrev_b32_e32 v140, 16, v131
	v_and_b32_e32 v139, 0xffff0000, v139
	v_fma_f32 v141, v60, v138, v61
	v_fma_f32 v137, v60, v137, v61
	v_and_b32_e32 v142, 0xffff0000, v115
	v_cmp_gt_i32_e32 vcc, s77, v252
	v_fma_f32 v143, v60, v136, v61
	v_fmac_f32_e32 v141, v63, v136
	v_fma_f32 v254, v60, v139, v61
	v_fmac_f32_e32 v137, v63, v138
	v_cndmask_b32_e32 v140, 0, v140, vcc
	v_fmac_f32_e32 v143, v63, v139
	v_fmac_f32_e32 v141, v64, v139
	v_fmac_f32_e32 v254, v63, v142
	v_fmac_f32_e32 v137, v64, v136
	v_fmac_f32_e32 v143, v64, v142
	v_mul_f32_e32 v1, v1, v141
	v_fmac_f32_e32 v254, v64, v140
	v_mul_f32_e32 v0, v0, v137
	v_mul_f32_e32 v2, v143, v2
	v_mul_f32_e32 v3, v3, v254
	v_lshlrev_b32_e32 v132, 1, v252
	v_mov_b32_e32 v133, 0
	v_cvt_pk_bf16_f32 v0, v0, v1
	v_cvt_pk_bf16_f32 v1, v2, v3
	v_lshl_add_u64 v[134:135], v[58:59], 0, v[132:133]
	global_store_dwordx2 v[134:135], v[0:1], off
	s_andn2_b64 vcc, exec, s[6:7]
	s_mov_b64 s[6:7], 0
	s_cbranch_vccnz .LBB0_658
	s_barrier
	s_branch .LBB0_505

; __device__ __forceinline__ int otid() { int t = threadIdx.x; asm volatile("" : "+v"(t)); return t; }
; __device__ __forceinline__ void g3_epi(const Params& p, int mt, int nt, f32x4 (&acc)[8][4]) {
;   const int tid = otid(), lane = tid & 63, wave = tid >> 6;
;   const int wm = wave >> 2, wn = wave & 3, lr = lane & 15, lq = lane >> 4;
;   const float* x = p.in[0];
;   const float* modx = (const float*)(p.ws + OFF_MODX);
;   const int b = mt >> 3;
;   const int n0 = nt * 256 + wn * 64 + lq * 16;
;   float4 g1v[4];
; #pragma unroll
;   for (int j = 0; j < 4; ++j) g1v[j] = *(const float4*)(modx + b * 6144 + 2048 + n0 + j * 4);
; #pragma unroll
;   for (int i = 0; i < 8; ++i) {
;     const int m = mt * 256 + wm * 128 + i * 16 + lr;
; #pragma unroll
;     for (int j = 0; j < 4; ++j) {
;       const float4 xv = *(const float4*)(x + (size_t)m * 1024 + n0 + j * 4);
;       float4 o;
;       o.x = xv.x + g1v[j].x * acc[i][j][0]; o.y = xv.y + g1v[j].y * acc[i][j][1];
;       o.z = xv.z + g1v[j].z * acc[i][j][2]; o.w = xv.w + g1v[j].w * acc[i][j][3];
;       *(float4*)(p.out + (size_t)m * 1024 + n0 + j * 4) = o;
;     }
;   }
; }
.LBB0_937:
	v_mov_b32_e32 v130, v153
	s_lshl_b32 s40, s56, 8
	s_lshr_b32 s39, s56, 5
	s_and_b32 s40, s40, 0x300
	v_and_b32_e32 v128, 0xf0, v130
	v_or_b32_e32 v128, s40, v128
	s_mul_i32 s40, s39, 0x1800
	s_ashr_i32 s41, s40, 31
	s_lshl_b64 s[40:41], s[40:41], 2
	s_add_u32 s40, s46, s40
	s_addc_u32 s41, s47, s41
	s_lshl_b32 s39, s56, 6
	v_ashrrev_i32_e32 v131, 1, v130
	s_and_b32 s39, s39, 0xffffff00
	v_and_b32_e32 v131, 0xffffff80, v131
	v_lshlrev_b32_e32 v144, 2, v128
	v_add_u32_e32 v131, s39, v131
	v_lshl_add_u64 v[128:129], s[40:41], 0, v[144:145]
	v_and_or_b32 v162, v130, 15, v131
	v_ashrrev_i32_e32 v163, 31, v162
	v_add_co_u32_e32 v130, vcc, s55, v128
	v_lshl_add_u64 v[160:161], s[16:17], 0, v[144:145]
	v_lshlrev_b64 v[170:171], 12, v[162:163]
	v_addc_co_u32_e32 v131, vcc, 0, v129, vcc
	v_lshl_add_u64 v[172:173], v[160:161], 0, v[170:171]
	global_load_dwordx4 v[132:135], v[130:131], off
	v_lshl_add_u64 v[170:171], s[44:45], 0, v[170:171]
	v_lshl_add_u64 v[140:141], v[128:129], 0, s[34:35]
	v_lshl_add_u64 v[170:171], v[170:171], 0, v[144:145]
	global_load_dwordx4 v[128:131], v[140:141], off offset:48
	global_load_dwordx4 v[136:139], v[140:141], off offset:32
	global_load_dwordx4 v[140:143], v[140:141], off offset:16
	s_mov_b32 s98, 0x10000
	s_mov_b32 s99, 0
	global_load_dwordx4 v[236:239], v[172:173], off
	global_load_dwordx4 v[240:243], v[172:173], off offset:16
	global_load_dwordx4 v[244:247], v[172:173], off offset:32
	global_load_dwordx4 v[248:251], v[172:173], off offset:48
	v_lshl_add_u64 v[172:173], v[172:173], 0, s[98:99]
	s_waitcnt vmcnt(0)
	v_pk_fma_f32 v[124:125], v[124:125], v[132:133], v[236:237]
	v_pk_fma_f32 v[126:127], v[126:127], v[134:135], v[238:239]
	v_pk_fma_f32 v[120:121], v[120:121], v[140:141], v[240:241]
	v_pk_fma_f32 v[122:123], v[122:123], v[142:143], v[242:243]
	v_pk_fma_f32 v[116:117], v[116:117], v[136:137], v[244:245]
	v_pk_fma_f32 v[118:119], v[118:119], v[138:139], v[246:247]
	v_pk_fma_f32 v[112:113], v[112:113], v[128:129], v[248:249]
	v_pk_fma_f32 v[114:115], v[114:115], v[130:131], v[250:251]
	global_load_dwordx4 v[236:239], v[172:173], off
	global_load_dwordx4 v[240:243], v[172:173], off offset:16
	global_load_dwordx4 v[244:247], v[172:173], off offset:32
	global_load_dwordx4 v[248:251], v[172:173], off offset:48
	v_lshl_add_u64 v[172:173], v[172:173], 0, s[98:99]
	global_store_dwordx4 v[170:171], v[124:127], off
	global_store_dwordx4 v[170:171], v[120:123], off offset:16
	global_store_dwordx4 v[170:171], v[116:119], off offset:32
	global_store_dwordx4 v[170:171], v[112:115], off offset:48
	v_lshl_add_u64 v[170:171], v[170:171], 0, s[98:99]
	s_nop 1
	global_load_dwordx4 v[124:127], v[172:173], off
	global_load_dwordx4 v[120:123], v[172:173], off offset:16
	global_load_dwordx4 v[116:119], v[172:173], off offset:32
	global_load_dwordx4 v[112:115], v[172:173], off offset:48
	v_lshl_add_u64 v[172:173], v[172:173], 0, s[98:99]
	s_waitcnt vmcnt(8)
	v_pk_fma_f32 v[108:109], v[108:109], v[132:133], v[236:237]
	v_pk_fma_f32 v[110:111], v[110:111], v[134:135], v[238:239]
	v_pk_fma_f32 v[104:105], v[104:105], v[140:141], v[240:241]
	v_pk_fma_f32 v[106:107], v[106:107], v[142:143], v[242:243]
	v_pk_fma_f32 v[100:101], v[100:101], v[136:137], v[244:245]
	v_pk_fma_f32 v[102:103], v[102:103], v[138:139], v[246:247]
	v_pk_fma_f32 v[96:97], v[96:97], v[128:129], v[248:249]
	v_pk_fma_f32 v[98:99], v[98:99], v[130:131], v[250:251]
	global_store_dwordx4 v[170:171], v[108:111], off
	global_store_dwordx4 v[170:171], v[104:107], off offset:16
	global_store_dwordx4 v[170:171], v[100:103], off offset:32
	global_store_dwordx4 v[170:171], v[96:99], off offset:48
	v_lshl_add_u64 v[170:171], v[170:171], 0, s[98:99]
	s_nop 1
	global_load_dwordx4 v[236:239], v[172:173], off
	global_load_dwordx4 v[240:243], v[172:173], off offset:16
	global_load_dwordx4 v[244:247], v[172:173], off offset:32
	global_load_dwordx4 v[248:251], v[172:173], off offset:48
	v_lshl_add_u64 v[172:173], v[172:173], 0, s[98:99]
	s_waitcnt vmcnt(8)
	v_pk_fma_f32 v[92:93], v[92:93], v[132:133], v[124:125]
	v_pk_fma_f32 v[94:95], v[94:95], v[134:135], v[126:127]
	v_pk_fma_f32 v[88:89], v[88:89], v[140:141], v[120:121]
	v_pk_fma_f32 v[90:91], v[90:91], v[142:143], v[122:123]
	v_pk_fma_f32 v[84:85], v[84:85], v[136:137], v[116:117]
	v_pk_fma_f32 v[86:87], v[86:87], v[138:139], v[118:119]
	v_pk_fma_f32 v[80:81], v[80:81], v[128:129], v[112:113]
	v_pk_fma_f32 v[82:83], v[82:83], v[130:131], v[114:115]
	global_store_dwordx4 v[170:171], v[92:95], off
	global_store_dwordx4 v[170:171], v[88:91], off offset:16
	global_store_dwordx4 v[170:171], v[84:87], off offset:32
	global_store_dwordx4 v[170:171], v[80:83], off offset:48
	v_lshl_add_u64 v[170:171], v[170:171], 0, s[98:99]
	s_nop 1
	global_load_dwordx4 v[108:111], v[172:173], off
	global_load_dwordx4 v[104:107], v[172:173], off offset:16
	global_load_dwordx4 v[100:103], v[172:173], off offset:32
	global_load_dwordx4 v[96:99], v[172:173], off offset:48
	v_lshl_add_u64 v[172:173], v[172:173], 0, s[98:99]
	s_waitcnt vmcnt(8)
; __device__ __forceinline__ int otid() { int t = threadIdx.x; asm volatile("" : "+v"(t)); return t; }
; __device__ __forceinline__ void g3_epi(const Params& p, int mt, int nt, f32x4 (&acc)[8][4]) {
;   const int tid = otid(), lane = tid & 63, wave = tid >> 6;
;   const int wm = wave >> 2, wn = wave & 3, lr = lane & 15, lq = lane >> 4;
;   const float* x = p.in[0];
;   const float* modx = (const float*)(p.ws + OFF_MODX);
;   const int b = mt >> 3;
;   const int n0 = nt * 256 + wn * 64 + lq * 16;
;   float4 g1v[4];
; #pragma unroll
;   for (int j = 0; j < 4; ++j) g1v[j] = *(const float4*)(modx + b * 6144 + 2048 + n0 + j * 4);
; #pragma unroll
;   for (int i = 0; i < 8; ++i) {
;     const int m = mt * 256 + wm * 128 + i * 16 + lr;
; #pragma unroll
;     for (int j = 0; j < 4; ++j) {
;       const float4 xv = *(const float4*)(x + (size_t)m * 1024 + n0 + j * 4);
;       float4 o;
;       o.x = xv.x + g1v[j].x * acc[i][j][0]; o.y = xv.y + g1v[j].y * acc[i][j][1];
;       o.z = xv.z + g1v[j].z * acc[i][j][2]; o.w = xv.w + g1v[j].w * acc[i][j][3];
;       *(float4*)(p.out + (size_t)m * 1024 + n0 + j * 4) = o;
;     }
;   }
; }
	v_pk_fma_f32 v[76:77], v[76:77], v[132:133], v[236:237]
	v_pk_fma_f32 v[78:79], v[78:79], v[134:135], v[238:239]
	v_pk_fma_f32 v[72:73], v[72:73], v[140:141], v[240:241]
	v_pk_fma_f32 v[74:75], v[74:75], v[142:143], v[242:243]
	v_pk_fma_f32 v[68:69], v[68:69], v[136:137], v[244:245]
	v_pk_fma_f32 v[70:71], v[70:71], v[138:139], v[246:247]
	v_pk_fma_f32 v[64:65], v[64:65], v[128:129], v[248:249]
	v_pk_fma_f32 v[66:67], v[66:67], v[130:131], v[250:251]
	global_store_dwordx4 v[170:171], v[76:79], off
	global_store_dwordx4 v[170:171], v[72:75], off offset:16
	global_store_dwordx4 v[170:171], v[68:71], off offset:32
	global_store_dwordx4 v[170:171], v[64:67], off offset:48
	v_lshl_add_u64 v[170:171], v[170:171], 0, s[98:99]
	s_nop 1
	global_load_dwordx4 v[236:239], v[172:173], off
	global_load_dwordx4 v[240:243], v[172:173], off offset:16
	global_load_dwordx4 v[244:247], v[172:173], off offset:32
	global_load_dwordx4 v[248:251], v[172:173], off offset:48
	v_lshl_add_u64 v[172:173], v[172:173], 0, s[98:99]
	s_waitcnt vmcnt(8)
	v_pk_fma_f32 v[60:61], v[60:61], v[132:133], v[108:109]
	v_pk_fma_f32 v[62:63], v[62:63], v[134:135], v[110:111]
	v_pk_fma_f32 v[56:57], v[56:57], v[140:141], v[104:105]
	v_pk_fma_f32 v[58:59], v[58:59], v[142:143], v[106:107]
	v_pk_fma_f32 v[52:53], v[52:53], v[136:137], v[100:101]
	v_pk_fma_f32 v[54:55], v[54:55], v[138:139], v[102:103]
	v_pk_fma_f32 v[48:49], v[48:49], v[128:129], v[96:97]
	v_pk_fma_f32 v[50:51], v[50:51], v[130:131], v[98:99]
	global_store_dwordx4 v[170:171], v[60:63], off
	global_store_dwordx4 v[170:171], v[56:59], off offset:16
	global_store_dwordx4 v[170:171], v[52:55], off offset:32
	global_store_dwordx4 v[170:171], v[48:51], off offset:48
	v_lshl_add_u64 v[170:171], v[170:171], 0, s[98:99]
	s_nop 1
	global_load_dwordx4 v[92:95], v[172:173], off
	global_load_dwordx4 v[88:91], v[172:173], off offset:16
	global_load_dwordx4 v[84:87], v[172:173], off offset:32
	global_load_dwordx4 v[80:83], v[172:173], off offset:48
	v_lshl_add_u64 v[172:173], v[172:173], 0, s[98:99]
	s_waitcnt vmcnt(8)
	v_pk_fma_f32 v[44:45], v[44:45], v[132:133], v[236:237]
	v_pk_fma_f32 v[46:47], v[46:47], v[134:135], v[238:239]
	v_pk_fma_f32 v[40:41], v[40:41], v[140:141], v[240:241]
	v_pk_fma_f32 v[42:43], v[42:43], v[142:143], v[242:243]
	v_pk_fma_f32 v[36:37], v[36:37], v[136:137], v[244:245]
	v_pk_fma_f32 v[38:39], v[38:39], v[138:139], v[246:247]
	v_pk_fma_f32 v[32:33], v[32:33], v[128:129], v[248:249]
	v_pk_fma_f32 v[34:35], v[34:35], v[130:131], v[250:251]
	global_store_dwordx4 v[170:171], v[44:47], off
	global_store_dwordx4 v[170:171], v[40:43], off offset:16
	global_store_dwordx4 v[170:171], v[36:39], off offset:32
	global_store_dwordx4 v[170:171], v[32:35], off offset:48
	v_lshl_add_u64 v[170:171], v[170:171], 0, s[98:99]
	s_nop 1
	global_load_dwordx4 v[236:239], v[172:173], off
	global_load_dwordx4 v[240:243], v[172:173], off offset:16
	global_load_dwordx4 v[244:247], v[172:173], off offset:32
	global_load_dwordx4 v[248:251], v[172:173], off offset:48
	v_lshl_add_u64 v[172:173], v[172:173], 0, s[98:99]
	s_waitcnt vmcnt(8)
	v_pk_fma_f32 v[28:29], v[28:29], v[132:133], v[92:93]
	v_pk_fma_f32 v[30:31], v[30:31], v[134:135], v[94:95]
	v_pk_fma_f32 v[24:25], v[24:25], v[140:141], v[88:89]
	v_pk_fma_f32 v[26:27], v[26:27], v[142:143], v[90:91]
	v_pk_fma_f32 v[20:21], v[20:21], v[136:137], v[84:85]
	v_pk_fma_f32 v[22:23], v[22:23], v[138:139], v[86:87]
	v_pk_fma_f32 v[16:17], v[16:17], v[128:129], v[80:81]
	v_pk_fma_f32 v[18:19], v[18:19], v[130:131], v[82:83]
	global_store_dwordx4 v[170:171], v[28:31], off
	global_store_dwordx4 v[170:171], v[24:27], off offset:16
	global_store_dwordx4 v[170:171], v[20:23], off offset:32
	global_store_dwordx4 v[170:171], v[16:19], off offset:48
	v_lshl_add_u64 v[170:171], v[170:171], 0, s[98:99]
	s_waitcnt vmcnt(4)
	v_pk_fma_f32 v[12:13], v[12:13], v[132:133], v[236:237]
	v_pk_fma_f32 v[14:15], v[14:15], v[134:135], v[238:239]
	v_pk_fma_f32 v[8:9], v[8:9], v[140:141], v[240:241]
	v_pk_fma_f32 v[10:11], v[10:11], v[142:143], v[242:243]
	v_pk_fma_f32 v[4:5], v[4:5], v[136:137], v[244:245]
	v_pk_fma_f32 v[6:7], v[6:7], v[138:139], v[246:247]
	v_pk_fma_f32 v[0:1], v[0:1], v[128:129], v[248:249]
	v_pk_fma_f32 v[2:3], v[2:3], v[130:131], v[250:251]
	global_store_dwordx4 v[170:171], v[12:15], off
	global_store_dwordx4 v[170:171], v[8:11], off offset:16
	global_store_dwordx4 v[170:171], v[4:7], off offset:32
	global_store_dwordx4 v[170:171], v[0:3], off offset:48
	v_lshl_add_u64 v[170:171], v[170:171], 0, s[98:99]
	s_and_b64 vcc, exec, s[36:37]
	s_cbranch_vccnz .LBB0_928
